# SB attention: K tile in LDS swizzled by row&15 (2-way bank conflict on the QK^T A-operand reads removed, as done for MLA)
# speedup vs baseline: 1.0015x; 1.0015x over previous
.LBB0_682:
	v_writelane_b32 v246, s60, 8
	s_nop 1
	v_writelane_b32 v246, s61, 9
	v_writelane_b32 v246, s72, 10
	s_or_b64 exec, exec, s[4:5]
	s_cmpk_gt_i32 s2, 0x3ff
	s_waitcnt lgkmcnt(0)
	s_barrier
	s_cbranch_scc1 .LBB0_831
	s_lshl_b32 s72, s2, 8
	s_lshl_b32 s73, s3, 8
	s_movk_i32 s78, 0xf0
	v_mov_b32_e32 v1, 0
	s_mov_b32 s79, 0xc32a0000
	v_mbcnt_hi_u32_b32 v167, -1, v180
	s_mov_b32 s81, s2
	s_branch .LBB0_685

.LBB0_685:
	s_mov_b64 s[4:5], s[0:1]
	s_load_dwordx2 s[4:5], s[4:5], 0xa8
	s_ashr_i32 s88, s81, 5
	s_lshl_b32 s6, s81, 8
	s_ashr_i32 s89, s88, 31
	s_and_b32 s83, s6, 0x1f00
	s_lshl_b64 s[70:71], s[88:89], 21
	s_lshl_b32 s6, s83, 8
	s_waitcnt lgkmcnt(0)
	s_add_u32 s4, s4, s70
	s_addc_u32 s7, s5, s71
	s_add_u32 s6, s4, s6
	s_mov_b64 s[4:5], s[0:1]
	s_load_dwordx2 s[4:5], s[4:5], 0xa8
	s_mov_b64 s[8:9], s[0:1]
	s_addc_u32 s7, s7, 0
	s_load_dwordx2 s[8:9], s[8:9], 0xa8
	s_waitcnt lgkmcnt(0)
	s_add_u32 s94, s4, 0x14000000
	s_addc_u32 s95, s5, 0
	s_add_u32 s4, s94, s70
	s_addc_u32 s5, s95, s71
	s_add_u32 s96, s8, 0x18000000
	s_addc_u32 s97, s9, 0
	s_mov_b64 s[10:11], s[0:1]
	s_add_u32 s8, s96, s70
	v_mov_b32_e32 v181, v178
	s_addc_u32 s9, s97, s71
	s_load_dwordx2 s[90:91], s[10:11], 0xa8
	s_or_b32 s10, s83, 0xc0
	v_ashrrev_i32_e32 v66, 4, v181
	v_add_u32_e32 v20, s10, v66
	v_lshlrev_b32_e32 v26, 3, v181
	v_ashrrev_i32_e32 v21, 31, v20
	v_and_b32_e32 v0, 0x78, v26
	v_lshlrev_b64 v[10:11], 8, v[20:21]
	v_lshlrev_b32_e32 v18, 1, v0
	v_lshl_add_u64 v[2:3], s[8:9], 0, v[10:11]
	v_mov_b32_e32 v19, v1
	v_add_u32_e32 v0, s83, v66
	v_lshl_add_u64 v[12:13], v[2:3], 0, v[18:19]
	v_add_u32_e32 v2, 0xe0, v0
	v_ashrrev_i32_e32 v3, 31, v2
	v_lshlrev_b64 v[14:15], 8, v[2:3]
	v_lshl_add_u64 v[2:3], s[8:9], 0, v[14:15]
	v_lshl_add_u64 v[10:11], s[4:5], 0, v[10:11]
	v_lshl_add_u64 v[16:17], v[2:3], 0, v[18:19]
	global_load_dwordx4 v[2:5], v[12:13], off
	global_load_dwordx4 v[6:9], v[16:17], off
	v_lshl_add_u64 v[22:23], v[10:11], 0, v[18:19]
	v_lshl_add_u64 v[10:11], s[4:5], 0, v[14:15]
	v_lshl_add_u64 v[24:25], v[10:11], 0, v[18:19]
	global_load_dwordx4 v[10:13], v[22:23], off
	global_load_dwordx4 v[14:17], v[24:25], off
	v_and_b32_e32 v0, 0xfffff0, v66
	v_lshlrev_b32_e32 v21, 1, v66
	v_and_or_b32 v0, v21, 8, v0
	v_lshrrev_b32_e32 v0, 1, v0
	v_bfe_u32 v22, v26, 5, 2
	v_lshrrev_b32_e32 v21, 1, v66
	v_or_b32_e32 v27, v0, v22
	v_and_b32_e32 v0, 3, v66
	v_and_or_b32 v21, v21, 4, v0
	v_add_u32_e32 v0, 32, v66
	v_readfirstlane_b32 s11, v181
	v_and_b32_e32 v23, 0xfffff0, v0
	v_lshlrev_b32_e32 v0, 1, v0
	s_ashr_i32 s76, s11, 6
	v_and_or_b32 v0, v0, 8, v23
	v_and_b32_e32 v182, 31, v181
	v_lshrrev_b32_e32 v0, 1, v0
	s_lshl_b32 s92, s76, 5
	v_or_b32_e32 v28, v0, v22
	v_or_b32_e32 v22, s92, v182
	v_ashrrev_i32_e32 v23, 31, v22
	v_bfe_u32 v183, v181, 5, 1
	v_lshlrev_b64 v[22:23], 8, v[22:23]
	v_lshl_add_u64 v[22:23], s[6:7], 0, v[22:23]
	v_lshlrev_b32_e32 v0, 4, v183
	v_lshl_add_u64 v[22:23], v[22:23], 0, v[0:1]
	s_mov_b64 s[6:7], 0x10000000
	v_lshl_add_u64 v[24:25], v[22:23], 0, s[6:7]
	s_brev_b32 s6, 8
	v_lshlrev_b32_e32 v185, 9, v27
	v_and_b32_e32 v186, 48, v18
	v_lshl_add_u32 v189, v21, 6, 0
	v_add_co_u32_e32 v22, vcc, s6, v22
	v_lshlrev_b32_e32 v187, 9, v28
	v_add3_u32 v21, v189, v185, v186
	v_bitop3_b32 v184, v18, v181, s78 bitop3:0x78
	v_addc_co_u32_e32 v23, vcc, 0, v23, vcc
	global_load_dwordx4 v[98:101], v[24:25], off offset:32
	global_load_dwordx4 v[102:105], v[24:25], off offset:64
	global_load_dwordx4 v[106:109], v[24:25], off offset:96
	global_load_dwordx4 v[110:113], v[24:25], off offset:128
	global_load_dwordx4 v[114:117], v[24:25], off offset:160
	global_load_dwordx4 v[118:121], v[24:25], off offset:192
	global_load_dwordx4 v[122:125], v[22:23], off
	global_load_dwordx4 v[126:129], v[24:25], off offset:224
	v_lshlrev_b32_e32 v188, 8, v66
	s_waitcnt vmcnt(0)
	v_lshl_add_u64 v[22:23], s[8:9], 0, v[18:19]
	v_lshl_add_u64 v[18:19], s[4:5], 0, v[18:19]
	s_add_i32 s4, s92, s83
	s_or_b32 s85, s4, 31
	s_movk_i32 s5, 0x118
	s_cmp_lg_u32 0, -1
	v_and_b32_e32 v67, 63, v181
	v_or_b32_e32 v190, s4, v182
	s_movk_i32 s4, 0x60
	s_cselect_b32 s6, 0, 0
	v_lshlrev_b32_e32 v191, 8, v182
	v_lshlrev_b32_e32 v196, 2, v183
	s_cmp_ge_i32 s10, s85
	s_waitcnt vmcnt(11)
	ds_write_b128 v21, v[2:5]
	v_add3_u32 v2, v189, v187, v186
	s_waitcnt vmcnt(10)
	ds_write_b128 v2, v[6:9]
	v_add3_u32 v2, 0, v188, v184
	s_waitcnt vmcnt(9)
	ds_write_b128 v2, v[10:13] offset:32768
	s_waitcnt vmcnt(8)
	ds_write_b128 v2, v[14:17] offset:40960
	v_subrev_u32_e32 v2, 64, v20
	v_ashrrev_i32_e32 v3, 31, v2
	v_subrev_u32_e32 v6, 32, v20
	v_lshlrev_b64 v[2:3], 8, v[2:3]
	v_ashrrev_i32_e32 v7, 31, v6
	v_lshl_add_u64 v[4:5], v[22:23], 0, v[2:3]
	v_lshlrev_b64 v[6:7], 8, v[6:7]
	v_lshl_add_u64 v[2:3], v[18:19], 0, v[2:3]
	s_waitcnt lgkmcnt(0)
	s_barrier
	v_lshl_add_u64 v[8:9], v[22:23], 0, v[6:7]
	global_load_dwordx4 v[130:133], v[4:5], off
	global_load_dwordx4 v[134:137], v[8:9], off
	v_lshl_add_u64 v[4:5], v[18:19], 0, v[6:7]
	global_load_dwordx4 v[138:141], v[2:3], off
	global_load_dwordx4 v[142:145], v[4:5], off
	v_lshlrev_b32_e32 v3, 1, v181
	v_lshlrev_b32_e32 v2, 4, v181
	v_and_b32_e32 v3, 32, v3
	v_and_b32_e32 v4, 0xc0, v2
	v_and_or_b32 v3, v26, s5, v3
	v_and_b32_e32 v5, 0xf0, v2
	v_bitop3_b32 v192, v0, v2, s78 bitop3:0x78
	v_bitop3_b32 v193, v0, v5, 32 bitop3:0x36
	v_bitop3_b32 v194, v0, v5, 64 bitop3:0x36
	v_bitop3_b32 v195, v0, v5, s4 bitop3:0x36
	v_cmp_gt_u32_e64 s[4:5], 32, v67
	v_add3_u32 v197, v4, s6, v3
	s_cbranch_scc1 .LBB0_687
	v_add3_u32 v0, 0, v192, v191
	ds_read_b128 v[2:5], v0 offset:32768
	ds_read_b128 v[6:9], v0 offset:40960
	v_add3_u32 v42, 0, v193, v191
	ds_read_b128 v[34:37], v42 offset:32768
	ds_read_b128 v[38:41], v42 offset:40960
	v_add3_u32 v43, 0, v194, v191
	s_waitcnt vmcnt(5) lgkmcnt(3)
	v_mfma_f32_32x32x16_bf16 v[18:33], v[2:5], v[122:125], 0
	v_add3_u32 v44, 0, v195, v191
	s_waitcnt lgkmcnt(2)
	v_mfma_f32_32x32x16_bf16 v[2:17], v[6:9], v[122:125], 0
	s_waitcnt lgkmcnt(1)
	v_mfma_f32_32x32x16_bf16 v[18:33], v[34:37], v[98:101], v[18:33]
	s_waitcnt lgkmcnt(0)
	v_mfma_f32_32x32x16_bf16 v[2:17], v[38:41], v[98:101], v[2:17]
	ds_read_b128 v[34:37], v43 offset:32768
	ds_read_b128 v[38:41], v43 offset:40960
	s_waitcnt lgkmcnt(1)
	v_mfma_f32_32x32x16_bf16 v[18:33], v[34:37], v[102:105], v[18:33]
	s_waitcnt lgkmcnt(0)
	v_mfma_f32_32x32x16_bf16 v[2:17], v[38:41], v[102:105], v[2:17]
	ds_read_b128 v[34:37], v44 offset:32768
	ds_read_b128 v[38:41], v44 offset:40960
	s_waitcnt lgkmcnt(1)
	v_mfma_f32_32x32x16_bf16 v[18:33], v[34:37], v[106:109], v[18:33]
	s_waitcnt lgkmcnt(0)
	v_mfma_f32_32x32x16_bf16 v[2:17], v[38:41], v[106:109], v[2:17]
	v_xor_b32_e32 v234, 0x80, v0
	ds_read_b128 v[34:37], v234 offset:32768
	ds_read_b128 v[38:41], v234 offset:40960
	v_or_b32_e32 v0, s10, v196
	v_sub_u32_e32 v0, v190, v0
	v_cmp_lt_i32_e64 s[6:7], 32, v0
	v_cmp_lt_i32_e64 s[10:11], 33, v0
	v_cmp_lt_i32_e64 s[8:9], 1, v0
	v_cmp_lt_i32_e64 s[14:15], 34, v0
	s_waitcnt lgkmcnt(1)
	v_mfma_f32_32x32x16_bf16 v[18:33], v[34:37], v[110:113], v[18:33]
	v_cmp_lt_i32_e64 s[12:13], 2, v0
	v_cmp_lt_i32_e64 s[22:23], 35, v0
	v_cmp_lt_i32_e64 s[20:21], 3, v0
	v_cmp_lt_i32_e64 s[18:19], 40, v0
	v_cmp_lt_i32_e64 s[16:17], 8, v0
	v_cmp_lt_i32_e64 s[26:27], 41, v0
	v_cmp_lt_i32_e64 s[24:25], 9, v0
	s_waitcnt lgkmcnt(0)
	v_mfma_f32_32x32x16_bf16 v[2:17], v[38:41], v[110:113], v[2:17]
	v_xor_b32_e32 v234, 0x80, v42
	ds_read_b128 v[34:37], v234 offset:32768
	ds_read_b128 v[38:41], v234 offset:40960
	v_cmp_lt_i32_e64 s[30:31], 42, v0
	v_cmp_lt_i32_e64 s[28:29], 10, v0
	v_cmp_lt_i32_e64 s[40:41], 43, v0
	v_cmp_lt_i32_e64 s[38:39], 11, v0
	v_cmp_lt_i32_e64 s[36:37], 48, v0
	v_cmp_lt_i32_e64 s[34:35], 16, v0
	s_waitcnt lgkmcnt(1)
	v_mfma_f32_32x32x16_bf16 v[18:33], v[34:37], v[114:117], v[18:33]
	v_cmp_lt_i32_e64 s[44:45], 49, v0
	v_cmp_lt_i32_e64 s[42:43], 17, v0
	v_cmp_lt_i32_e64 s[48:49], 50, v0
	v_cmp_lt_i32_e64 s[46:47], 18, v0
	v_cmp_lt_i32_e64 s[56:57], 51, v0
	v_cmp_lt_i32_e64 s[54:55], 19, v0
	v_cmp_lt_i32_e64 s[52:53], 56, v0
	s_waitcnt lgkmcnt(0)
	v_mfma_f32_32x32x16_bf16 v[2:17], v[38:41], v[114:117], v[2:17]
	v_xor_b32_e32 v234, 0x80, v43
	ds_read_b128 v[34:37], v234 offset:32768
	ds_read_b128 v[38:41], v234 offset:40960
	v_cmp_lt_i32_e64 s[50:51], 24, v0
	v_cmp_lt_i32_e64 s[60:61], 57, v0
	v_cmp_lt_i32_e64 s[58:59], 25, v0
	v_cmp_lt_i32_e64 s[64:65], 58, v0
	v_cmp_lt_i32_e64 s[62:63], 26, v0
	v_cmp_lt_i32_e64 s[66:67], 27, v0
	s_waitcnt lgkmcnt(1)
	v_mfma_f32_32x32x16_bf16 v[18:33], v[34:37], v[118:121], v[18:33]
	v_cmp_lt_i32_e32 vcc, 0, v0
	v_cmp_lt_i32_e64 s[68:69], 59, v0
	s_waitcnt lgkmcnt(0)
	v_mfma_f32_32x32x16_bf16 v[2:17], v[38:41], v[118:121], v[2:17]
	v_xor_b32_e32 v234, 0x80, v44
	ds_read_b128 v[34:37], v234 offset:32768
	ds_read_b128 v[38:41], v234 offset:40960
	s_waitcnt vmcnt(4) lgkmcnt(1)
	v_mfma_f32_32x32x16_bf16 v[18:33], v[34:37], v[126:129], v[18:33]
	s_waitcnt lgkmcnt(0)
	v_mfma_f32_32x32x16_bf16 v[2:17], v[38:41], v[126:129], v[2:17]
	s_nop 9
	v_exp_f32_e64 v35, -|v18|
	v_max_f32_e32 v34, 0, v18
	v_add_f32_e32 v35, 1.0, v35
	v_log_f32_e32 v35, v35
	v_exp_f32_e64 v36, -|v2|
	v_exp_f32_e64 v37, -|v3|
	v_add_f32_e32 v34, v34, v35
	v_add_f32_e32 v36, 1.0, v36
	v_log_f32_e32 v36, v36
	v_max_f32_e32 v35, 0, v2
	v_add_f32_e32 v37, 1.0, v37
	v_log_f32_e32 v37, v37
	v_add_f32_e32 v35, v35, v36
	v_exp_f32_e64 v36, -|v19|
	v_cndmask_b32_e64 v56, 0, -v35, s[6:7]
	v_max_f32_e32 v35, 0, v19
	v_add_f32_e32 v36, 1.0, v36
	v_log_f32_e32 v36, v36
	v_exp_f32_e64 v38, -|v4|
	v_exp_f32_e64 v39, -|v5|
	v_cndmask_b32_e64 v34, 0, -v34, vcc
	v_add_f32_e32 v35, v35, v36
	v_max_f32_e32 v36, 0, v3
	v_add_f32_e32 v37, v36, v37
	v_cndmask_b32_e64 v57, 0, -v37, s[10:11]
	v_exp_f32_e64 v37, -|v20|
	v_add_f32_e32 v38, 1.0, v38
	v_cndmask_b32_e64 v36, 0, -v35, s[8:9]
	v_add_f32_e32 v37, 1.0, v37
	v_log_f32_e32 v37, v37
	v_log_f32_e32 v38, v38
	v_max_f32_e32 v35, 0, v20
	v_add_f32_e32 v39, 1.0, v39
	v_add_f32_e32 v35, v35, v37
	v_max_f32_e32 v37, 0, v4
	v_add_f32_e32 v37, v37, v38
	v_cndmask_b32_e64 v58, 0, -v37, s[14:15]
	v_exp_f32_e64 v37, -|v21|
	v_cndmask_b32_e64 v38, 0, -v35, s[12:13]
	v_log_f32_e32 v39, v39
	v_add_f32_e32 v37, 1.0, v37
	v_log_f32_e32 v37, v37
	v_max_f32_e32 v35, 0, v21
	v_add_f32_e32 v0, v56, v57
	v_add_f32_e32 v35, v35, v37
	v_max_f32_e32 v37, 0, v5
	v_add_f32_e32 v37, v37, v39
	v_cndmask_b32_e64 v61, 0, -v37, s[22:23]
	v_exp_f32_e64 v37, -|v22|
	v_exp_f32_e64 v39, -|v6|
	v_cndmask_b32_e64 v40, 0, -v35, s[20:21]
	v_add_f32_e32 v37, 1.0, v37
	v_log_f32_e32 v37, v37
	v_add_f32_e32 v39, 1.0, v39
	v_log_f32_e32 v39, v39
	v_max_f32_e32 v35, 0, v22
	v_add_f32_e32 v35, v35, v37
	v_max_f32_e32 v37, 0, v6
	v_add_f32_e32 v37, v37, v39
	v_cndmask_b32_e64 v60, 0, -v37, s[18:19]
	v_exp_f32_e64 v37, -|v23|
	v_exp_f32_e64 v39, -|v7|
	v_cndmask_b32_e64 v59, 0, -v35, s[16:17]
	v_add_f32_e32 v37, 1.0, v37
	v_log_f32_e32 v37, v37
	v_add_f32_e32 v39, 1.0, v39
	v_log_f32_e32 v39, v39
	v_max_f32_e32 v35, 0, v23
	v_add_f32_e32 v35, v35, v37
	v_max_f32_e32 v37, 0, v7
	v_add_f32_e32 v37, v37, v39
	v_cndmask_b32_e64 v63, 0, -v37, s[26:27]
	v_exp_f32_e64 v37, -|v24|
	v_exp_f32_e64 v39, -|v8|
	v_cndmask_b32_e64 v62, 0, -v35, s[24:25]
	v_add_f32_e32 v37, 1.0, v37
	v_log_f32_e32 v37, v37
	v_add_f32_e32 v39, 1.0, v39
	v_log_f32_e32 v39, v39
	v_max_f32_e32 v35, 0, v24
	v_add_f32_e32 v35, v35, v37
	v_max_f32_e32 v37, 0, v8
	v_add_f32_e32 v37, v37, v39
	v_cndmask_b32_e64 v65, 0, -v37, s[30:31]
	v_exp_f32_e64 v37, -|v25|
	v_exp_f32_e64 v39, -|v9|
	v_cndmask_b32_e64 v64, 0, -v35, s[28:29]
	v_add_f32_e32 v37, 1.0, v37
	v_log_f32_e32 v37, v37
	v_add_f32_e32 v39, 1.0, v39
	v_log_f32_e32 v39, v39
	v_max_f32_e32 v35, 0, v25
	v_add_f32_e32 v35, v35, v37
	v_max_f32_e32 v37, 0, v9
	v_add_f32_e32 v37, v37, v39
	v_cndmask_b32_e64 v70, 0, -v37, s[40:41]
	v_exp_f32_e64 v37, -|v26|
	v_exp_f32_e64 v39, -|v10|
	v_cndmask_b32_e64 v69, 0, -v35, s[38:39]
	v_add_f32_e32 v37, 1.0, v37
	v_log_f32_e32 v37, v37
	v_add_f32_e32 v39, 1.0, v39
	v_log_f32_e32 v39, v39
	v_max_f32_e32 v35, 0, v26
	v_add_f32_e32 v35, v35, v37
	v_max_f32_e32 v37, 0, v10
	v_add_f32_e32 v37, v37, v39
	v_cndmask_b32_e64 v42, 0, -v37, s[36:37]
	v_exp_f32_e64 v37, -|v27|
	v_exp_f32_e64 v39, -|v11|
	v_cndmask_b32_e64 v68, 0, -v35, s[34:35]
	v_add_f32_e32 v37, 1.0, v37
	v_log_f32_e32 v37, v37
	v_add_f32_e32 v39, 1.0, v39
	v_log_f32_e32 v39, v39
	v_max_f32_e32 v35, 0, v27
	v_add_f32_e32 v35, v35, v37
	v_max_f32_e32 v37, 0, v11
	v_add_f32_e32 v37, v37, v39
	v_cndmask_b32_e64 v44, 0, -v37, s[44:45]
	v_exp_f32_e64 v37, -|v28|
	v_exp_f32_e64 v39, -|v12|
	v_cndmask_b32_e64 v71, 0, -v35, s[42:43]
	v_add_f32_e32 v37, 1.0, v37
	v_log_f32_e32 v37, v37
	v_add_f32_e32 v39, 1.0, v39
	v_log_f32_e32 v39, v39
	v_max_f32_e32 v35, 0, v28
	v_add_f32_e32 v35, v35, v37
	v_max_f32_e32 v37, 0, v12
	v_add_f32_e32 v37, v37, v39
	v_cndmask_b32_e64 v73, 0, -v37, s[48:49]
	v_exp_f32_e64 v37, -|v29|
	v_exp_f32_e64 v39, -|v13|
	v_cndmask_b32_e64 v72, 0, -v35, s[46:47]
	v_add_f32_e32 v37, 1.0, v37
	v_log_f32_e32 v37, v37
	v_add_f32_e32 v39, 1.0, v39
	v_log_f32_e32 v39, v39
	v_max_f32_e32 v35, 0, v29
	v_add_f32_e32 v35, v35, v37
	v_max_f32_e32 v37, 0, v13
	v_add_f32_e32 v37, v37, v39
	v_cndmask_b32_e64 v76, 0, -v37, s[56:57]
	v_exp_f32_e64 v37, -|v30|
	v_exp_f32_e64 v39, -|v14|
	v_cndmask_b32_e64 v75, 0, -v35, s[54:55]
	v_add_f32_e32 v37, 1.0, v37
	v_log_f32_e32 v37, v37
	v_add_f32_e32 v39, 1.0, v39
	v_log_f32_e32 v39, v39
	v_max_f32_e32 v35, 0, v30
	v_add_f32_e32 v35, v35, v37
	v_max_f32_e32 v37, 0, v14
	v_add_f32_e32 v37, v37, v39
	v_cndmask_b32_e64 v74, 0, -v37, s[52:53]
	v_exp_f32_e64 v37, -|v31|
	v_exp_f32_e64 v39, -|v15|
	v_cndmask_b32_e64 v46, 0, -v35, s[50:51]
	v_add_f32_e32 v37, 1.0, v37
	v_log_f32_e32 v37, v37
	v_add_f32_e32 v39, 1.0, v39
	v_log_f32_e32 v39, v39
	v_max_f32_e32 v35, 0, v31
	v_add_f32_e32 v35, v35, v37
	v_max_f32_e32 v37, 0, v15
	v_add_f32_e32 v37, v37, v39
	v_cndmask_b32_e64 v77, 0, -v37, s[60:61]
	v_exp_f32_e64 v37, -|v32|
	v_exp_f32_e64 v39, -|v16|
	v_cndmask_b32_e64 v48, 0, -v35, s[58:59]
	v_add_f32_e32 v37, 1.0, v37
	v_log_f32_e32 v37, v37
	v_add_f32_e32 v39, 1.0, v39
	v_log_f32_e32 v39, v39
	v_max_f32_e32 v35, 0, v32
	v_add_f32_e32 v35, v35, v37
	v_max_f32_e32 v37, 0, v16
	v_add_f32_e32 v37, v37, v39
	v_cndmask_b32_e64 v80, 0, -v37, s[64:65]
	v_exp_f32_e64 v37, -|v33|
	v_exp_f32_e64 v39, -|v17|
	v_cndmask_b32_e64 v50, 0, -v35, s[62:63]
	v_add_f32_e32 v37, 1.0, v37
	v_log_f32_e32 v37, v37
	v_add_f32_e32 v39, 1.0, v39
	v_log_f32_e32 v39, v39
	v_max_f32_e32 v35, 0, v33
	v_add_f32_e32 v35, v35, v37
	v_max_f32_e32 v37, 0, v17
	v_cndmask_b32_e64 v52, 0, -v35, s[66:67]
	v_add_f32_e32 v35, v58, v61
	v_add_f32_e32 v37, v37, v39
	v_add_f32_e32 v47, v0, v35
	v_add_f32_e32 v0, v59, v62
	v_add_f32_e32 v35, v64, v69
	v_cndmask_b32_e64 v81, 0, -v37, s[68:69]
	v_add_f32_e32 v35, v0, v35
	v_add_f32_e32 v0, v60, v63
	v_add_f32_e32 v37, v65, v70
	v_add_f32_e32 v39, v0, v37
	v_add_f32_e32 v0, v68, v71
	v_add_f32_e32 v37, v72, v75
	v_add_f32_e32 v82, v0, v37
	v_mov_b32_e32 v0, v35
	v_mov_b32_e32 v37, v35
	s_nop 1
	v_permlane32_swap_b32_e32 v0, v37
	v_cndmask_b32_e64 v37, v0, v37, s[4:5]
	v_mov_b32_e32 v0, v82
	v_mov_b32_e32 v41, v82
	s_nop 1
	v_permlane32_swap_b32_e32 v0, v41
	v_cndmask_b32_e64 v83, v0, v41, s[4:5]
	v_mov_b32_e32 v0, v47
	v_mov_b32_e32 v41, v47
	s_nop 1
	v_permlane32_swap_b32_e32 v0, v41
	v_add_f32_e32 v43, v74, v77
	v_add_f32_e32 v45, v80, v81
	v_cndmask_b32_e64 v49, v0, v41, s[4:5]
	v_mov_b32_e32 v0, v39
	v_mov_b32_e32 v41, v39
	s_nop 1
	v_permlane32_swap_b32_e32 v0, v41
	v_pk_add_f32 v[78:79], v[42:43], v[44:45]
	v_cndmask_b32_e64 v41, v0, v41, s[4:5]
	v_mov_b32_e32 v0, v79
	v_mov_b32_e32 v43, v79
	s_nop 1
	v_permlane32_swap_b32_e32 v0, v43
	v_add_f32_e32 v54, v73, v76
	v_cndmask_b32_e64 v55, v0, v43, s[4:5]
	v_pk_add_f32 v[78:79], v[78:79], v[54:55]
	v_add_f32_e32 v51, v39, v41
	v_mov_b32_e32 v0, v78
	v_mov_b32_e32 v43, v78
	s_nop 1
	v_permlane32_swap_b32_e32 v0, v43
	v_cndmask_b32_e64 v0, v0, v43, s[4:5]
	v_add_f32_e32 v43, 0, v55
	v_cndmask_b32_e64 v45, 0, v0, s[4:5]
	v_pk_add_f32 v[54:55], v[78:79], v[0:1]
	v_pk_add_f32 v[78:79], v[46:47], v[48:49]
	v_add_f32_e32 v0, v45, v55
	v_pk_add_f32 v[54:55], v[54:55], v[54:55] op_sel:[0,1] op_sel_hi:[1,0]
	v_cndmask_b32_e64 v45, 0, v41, s[4:5]
	v_mov_b32_e32 v53, v54
	v_add_f32_e32 v45, v45, v54
	v_pk_add_f32 v[54:55], v[50:51], v[52:53]
	v_cndmask_b32_e64 v39, 0, v49, s[4:5]
	v_pk_add_f32 v[78:79], v[78:79], v[54:55]
	v_cndmask_b32_e64 v53, 0, v37, s[4:5]
	v_mov_b32_e32 v41, v78
	v_mov_b32_e32 v47, v78
	s_nop 1
	v_permlane32_swap_b32_e32 v41, v47
	v_cndmask_b32_e64 v41, v41, v47, s[4:5]
	v_add_f32_e32 v47, v39, v55
	v_cndmask_b32_e64 v39, 0, v41, s[4:5]
	v_add_f32_e32 v49, v39, v79
	v_add_f32_e32 v39, v78, v41
	v_add_f32_e32 v41, v39, v79
	v_cndmask_b32_e64 v39, 0, v83, s[4:5]
	v_add_f32_e32 v51, v39, v41
	v_add_f32_e32 v39, v82, v83
	v_pk_add_f32 v[78:79], v[38:39], v[40:41]
	v_pk_add_f32 v[54:55], v[34:35], v[36:37]
	v_add_f32_e32 v0, v76, v0
	v_pk_add_f32 v[54:55], v[54:55], v[78:79]
	v_add_f32_e32 v13, v13, v0
	v_mov_b32_e32 v35, v54
	v_mov_b32_e32 v37, v54
	s_nop 1
	v_permlane32_swap_b32_e32 v35, v37
	v_cndmask_b32_e64 v35, v35, v37, s[4:5]
	v_cndmask_b32_e64 v39, 0, v35, s[4:5]
	v_add_f32_e32 v39, v39, v55
	v_add_f32_e32 v39, 0, v39
	v_add_f32_e32 v39, v40, v39
	v_add_f32_e32 v38, v38, v39
	v_add_f32_e32 v36, v36, v38
	v_add_f32_e32 v37, v53, v79
	v_add_f32_e32 v34, v34, v36
	v_add_f32_e32 v18, v18, v34
	v_add_f32_e32 v34, 0, v37
	v_add_f32_e32 v34, v69, v34
	v_add_f32_e32 v25, v25, v34
	v_add_f32_e32 v34, v64, v34
	v_add_f32_e32 v24, v24, v34
	v_add_f32_e32 v34, v62, v34
	v_add_f32_e32 v23, v23, v34
	v_add_f32_e32 v34, v59, v34
	v_add_f32_e32 v22, v22, v34
	v_add_f32_e32 v34, v75, v51
	v_add_f32_e32 v29, v29, v34
	v_add_f32_e32 v34, v72, v34
	v_add_f32_e32 v28, v28, v34
	v_add_f32_e32 v34, v71, v34
	v_add_f32_e32 v27, v27, v34
	v_add_f32_e32 v34, v68, v34
	v_add_f32_e32 v26, v26, v34
	v_add_f32_e32 v40, v61, v47
	v_exp_f32_e32 v26, v26
	v_add_f32_e32 v21, v21, v39
	v_add_f32_e32 v39, v58, v40
	v_add_f32_e32 v0, v73, v0
	v_add_f32_e32 v20, v20, v38
	v_add_f32_e32 v38, v57, v39
	v_add_f32_e32 v12, v12, v0
	v_add_f32_e32 v0, v44, v0
	v_cndmask_b32_e64 v43, 0, v43, s[4:5]
	v_add_f32_e32 v19, v19, v36
	v_add_f32_e32 v36, v56, v38
	v_add_f32_e32 v11, v11, v0
	v_add_f32_e32 v0, v42, v0
	v_add_f32_e32 v2, v2, v36
	v_add_f32_e32 v36, v70, v45
	v_add_f32_e32 v0, v10, v0
	v_cndmask_b32_e64 v10, 0, v26, s[34:35]
	v_add_f32_e32 v26, v52, v49
	v_add_f32_e32 v34, v81, v43
	v_add_f32_e32 v9, v9, v36
	v_add_f32_e32 v36, v65, v36
	v_add_f32_e32 v33, v33, v26
	v_add_f32_e32 v17, v17, v34
	v_add_f32_e32 v26, v50, v26
	v_add_f32_e32 v34, v80, v34
	v_add_f32_e32 v8, v8, v36
	v_add_f32_e32 v36, v63, v36
	v_add_f32_e32 v32, v32, v26
	v_add_f32_e32 v16, v16, v34
	v_add_f32_e32 v26, v48, v26
	v_add_f32_e32 v34, v77, v34
	v_add_f32_e32 v7, v7, v36
	v_add_f32_e32 v36, v60, v36
	v_add_f32_e32 v31, v31, v26
	v_add_f32_e32 v15, v15, v34
	v_add_f32_e32 v26, v46, v26
	v_add_f32_e32 v34, v74, v34
	v_exp_f32_e32 v21, v21
	v_add_f32_e32 v5, v5, v40
	v_exp_f32_e32 v20, v20
	v_add_f32_e32 v4, v4, v39
	v_exp_f32_e32 v19, v19
	v_add_f32_e32 v3, v3, v38
	v_exp_f32_e32 v18, v18
	v_exp_f32_e32 v25, v25
	v_exp_f32_e32 v24, v24
	v_exp_f32_e32 v23, v23
	v_exp_f32_e32 v22, v22
	v_add_f32_e32 v6, v6, v36
	v_add_f32_e32 v26, v30, v26
	v_add_f32_e32 v14, v14, v34
	v_exp_f32_e32 v5, v5
	v_exp_f32_e32 v4, v4
	v_exp_f32_e32 v3, v3
	v_exp_f32_e32 v2, v2
	v_exp_f32_e32 v9, v9
	v_exp_f32_e32 v8, v8
	v_exp_f32_e32 v7, v7
	v_exp_f32_e32 v6, v6
	v_exp_f32_e32 v29, v29
	v_exp_f32_e32 v13, v13
	v_exp_f32_e32 v28, v28
	v_exp_f32_e32 v12, v12
	v_exp_f32_e32 v27, v27
	v_exp_f32_e32 v11, v11
	v_exp_f32_e32 v0, v0
	v_exp_f32_e32 v33, v33
	v_exp_f32_e32 v17, v17
	v_exp_f32_e32 v32, v32
	v_exp_f32_e32 v16, v16
	v_exp_f32_e32 v31, v31
	v_exp_f32_e32 v15, v15
	v_exp_f32_e32 v26, v26
	v_exp_f32_e32 v14, v14
	v_add_f32_e32 v35, v54, v35
	v_cndmask_b32_e64 v21, 0, v21, s[20:21]
	v_cndmask_b32_e64 v20, 0, v20, s[12:13]
	v_cndmask_b32_e64 v19, 0, v19, s[8:9]
	v_cndmask_b32_e32 v18, 0, v18, vcc
	v_cndmask_b32_e64 v25, 0, v25, s[38:39]
	v_cndmask_b32_e64 v24, 0, v24, s[28:29]
	v_cndmask_b32_e64 v23, 0, v23, s[24:25]
	v_cndmask_b32_e64 v22, 0, v22, s[16:17]
	v_cndmask_b32_e64 v5, 0, v5, s[22:23]
	v_cndmask_b32_e64 v4, 0, v4, s[14:15]
	v_cndmask_b32_e64 v3, 0, v3, s[10:11]
	v_cndmask_b32_e64 v2, 0, v2, s[6:7]
	v_cndmask_b32_e64 v9, 0, v9, s[40:41]
	v_cndmask_b32_e64 v8, 0, v8, s[30:31]
	v_cndmask_b32_e64 v7, 0, v7, s[26:27]
	v_cndmask_b32_e64 v6, 0, v6, s[18:19]
	v_cndmask_b32_e64 v29, 0, v29, s[54:55]
	v_cndmask_b32_e64 v13, 0, v13, s[56:57]
	v_cndmask_b32_e64 v28, 0, v28, s[46:47]
	v_cndmask_b32_e64 v12, 0, v12, s[48:49]
	v_cndmask_b32_e64 v27, 0, v27, s[42:43]
	v_cndmask_b32_e64 v11, 0, v11, s[44:45]
	v_cndmask_b32_e64 v0, 0, v0, s[36:37]
	v_cndmask_b32_e64 v33, 0, v33, s[66:67]
	v_cndmask_b32_e64 v17, 0, v17, s[68:69]
	v_cndmask_b32_e64 v32, 0, v32, s[62:63]
	v_cndmask_b32_e64 v16, 0, v16, s[64:65]
	v_cndmask_b32_e64 v31, 0, v31, s[58:59]
	v_cndmask_b32_e64 v15, 0, v15, s[60:61]
	v_cndmask_b32_e64 v26, 0, v26, s[50:51]
	v_cndmask_b32_e64 v14, 0, v14, s[52:53]
	v_add_f32_e32 v92, v35, v55
	v_cvt_pk_bf16_f32 v50, v18, v19
	v_cvt_pk_bf16_f32 v51, v20, v21
	v_cvt_pk_bf16_f32 v52, v22, v23
	v_cvt_pk_bf16_f32 v53, v24, v25
	v_add_f32_e32 v198, 0, v92
	v_permlane32_swap_b32_e32 v50, v52
	v_permlane32_swap_b32_e32 v51, v53
	v_cvt_pk_bf16_f32 v68, v10, v27
	v_cvt_pk_bf16_f32 v69, v28, v29
	v_cvt_pk_bf16_f32 v70, v26, v31
	v_cvt_pk_bf16_f32 v71, v32, v33
	v_cvt_pk_bf16_f32 v72, v2, v3
	v_cvt_pk_bf16_f32 v73, v4, v5
	v_cvt_pk_bf16_f32 v74, v6, v7
	v_cvt_pk_bf16_f32 v75, v8, v9
	v_cvt_pk_bf16_f32 v76, v0, v11
	v_cvt_pk_bf16_f32 v77, v12, v13
	v_cvt_pk_bf16_f32 v78, v14, v15
	v_cvt_pk_bf16_f32 v79, v16, v17
	v_permlane32_swap_b32_e32 v68, v70
	v_permlane32_swap_b32_e32 v69, v71
	v_permlane32_swap_b32_e32 v72, v74
	v_permlane32_swap_b32_e32 v73, v75
	v_permlane32_swap_b32_e32 v76, v78
	v_permlane32_swap_b32_e32 v77, v79
	ds_read_b64_tr_b16 v[2:3], v197 offset:0
	ds_read_b64_tr_b16 v[4:5], v197 offset:0x800
	ds_read_b64_tr_b16 v[18:19], v197 offset:0x1000
	ds_read_b64_tr_b16 v[20:21], v197 offset:0x1800
	ds_read_b64_tr_b16 v[22:23], v197 offset:0x2000
	ds_read_b64_tr_b16 v[24:25], v197 offset:0x2800
	ds_read_b64_tr_b16 v[26:27], v197 offset:0x3000
	ds_read_b64_tr_b16 v[28:29], v197 offset:0x3800
	s_waitcnt lgkmcnt(0)
	s_nop 0
	v_mfma_f32_32x32x16_bf16 v[2:17], v[50:53], v[2:5], 0
	v_mfma_f32_32x32x16_bf16 v[2:17], v[68:71], v[18:21], v[2:17]
	ds_read_b64_tr_b16 v[18:19], v197 offset:0x200
	ds_read_b64_tr_b16 v[20:21], v197 offset:0xa00
	ds_read_b64_tr_b16 v[34:35], v197 offset:0x1200
	ds_read_b64_tr_b16 v[36:37], v197 offset:0x1a00
	ds_read_b64_tr_b16 v[38:39], v197 offset:0x2200
	ds_read_b64_tr_b16 v[40:41], v197 offset:0x2a00
	ds_read_b64_tr_b16 v[42:43], v197 offset:0x3200
	v_mfma_f32_32x32x16_bf16 v[2:17], v[72:75], v[22:25], v[2:17]
	ds_read_b64_tr_b16 v[44:45], v197 offset:0x3a00
	s_waitcnt lgkmcnt(0)
	v_mfma_f32_32x32x16_bf16 v[2:17], v[76:79], v[26:29], v[2:17]
	v_mfma_f32_32x32x16_bf16 v[18:33], v[50:53], v[18:21], 0
	v_mfma_f32_32x32x16_bf16 v[18:33], v[68:71], v[34:37], v[18:33]
	ds_read_b64_tr_b16 v[34:35], v197 offset:0x400
	ds_read_b64_tr_b16 v[36:37], v197 offset:0xc00
	ds_read_b64_tr_b16 v[54:55], v197 offset:0x1400
	ds_read_b64_tr_b16 v[56:57], v197 offset:0x1c00
	ds_read_b64_tr_b16 v[58:59], v197 offset:0x2400
	ds_read_b64_tr_b16 v[60:61], v197 offset:0x2c00
	ds_read_b64_tr_b16 v[62:63], v197 offset:0x3400
	v_mfma_f32_32x32x16_bf16 v[18:33], v[72:75], v[38:41], v[18:33]
	ds_read_b64_tr_b16 v[64:65], v197 offset:0x3c00
	s_waitcnt lgkmcnt(0)
	v_mfma_f32_32x32x16_bf16 v[18:33], v[76:79], v[42:45], v[18:33]
	v_mfma_f32_32x32x16_bf16 v[34:49], v[50:53], v[34:37], 0
	v_mfma_f32_32x32x16_bf16 v[34:49], v[68:71], v[54:57], v[34:49]
	ds_read_b64_tr_b16 v[54:55], v197 offset:0x600
	ds_read_b64_tr_b16 v[56:57], v197 offset:0xe00
	ds_read_b64_tr_b16 v[80:81], v197 offset:0x1600
	ds_read_b64_tr_b16 v[82:83], v197 offset:0x1e00
	ds_read_b64_tr_b16 v[84:85], v197 offset:0x2600
	ds_read_b64_tr_b16 v[86:87], v197 offset:0x2e00
	ds_read_b64_tr_b16 v[88:89], v197 offset:0x3600
	v_mfma_f32_32x32x16_bf16 v[34:49], v[72:75], v[58:61], v[34:49]
	ds_read_b64_tr_b16 v[90:91], v197 offset:0x3e00
	s_waitcnt lgkmcnt(0)
	v_mfma_f32_32x32x16_bf16 v[34:49], v[76:79], v[62:65], v[34:49]
	v_mfma_f32_32x32x16_bf16 v[50:65], v[50:53], v[54:57], 0
	v_cmp_gt_f32_e32 vcc, s79, v92
	s_cmp_eq_u64 vcc, exec
	s_cselect_b64 s[8:9], -1, 0
	v_mfma_f32_32x32x16_bf16 v[50:65], v[68:71], v[80:83], v[50:65]
	v_mfma_f32_32x32x16_bf16 v[50:65], v[72:75], v[84:87], v[50:65]
	v_mfma_f32_32x32x16_bf16 v[50:65], v[76:79], v[88:91], v[50:65]
	s_branch .LBB0_688

.LBB0_700:
	v_add3_u32 v0, s12, v192, v191
	ds_read_b128 v[66:69], v0 offset:32768
	ds_read_b128 v[70:73], v0 offset:40960
	v_add3_u32 v162, s12, v193, v191
	ds_read_b128 v[154:157], v162 offset:32768
	ds_read_b128 v[158:161], v162 offset:40960
	v_add3_u32 v163, s12, v194, v191
	s_waitcnt lgkmcnt(3)
	v_mfma_f32_32x32x16_bf16 v[82:97], v[66:69], v[122:125], 0
	v_add3_u32 v164, s12, v195, v191
	s_waitcnt lgkmcnt(2)
	v_mfma_f32_32x32x16_bf16 v[66:81], v[70:73], v[122:125], 0
	s_waitcnt lgkmcnt(1)
	v_mfma_f32_32x32x16_bf16 v[82:97], v[154:157], v[98:101], v[82:97]
	s_waitcnt lgkmcnt(0)
	v_mfma_f32_32x32x16_bf16 v[66:81], v[158:161], v[98:101], v[66:81]
	ds_read_b128 v[154:157], v163 offset:32768
	ds_read_b128 v[158:161], v163 offset:40960
	s_waitcnt lgkmcnt(1)
	v_mfma_f32_32x32x16_bf16 v[82:97], v[154:157], v[102:105], v[82:97]
	s_waitcnt lgkmcnt(0)
	v_mfma_f32_32x32x16_bf16 v[66:81], v[158:161], v[102:105], v[66:81]
	ds_read_b128 v[154:157], v164 offset:32768
	ds_read_b128 v[158:161], v164 offset:40960
	s_waitcnt lgkmcnt(1)
	v_mfma_f32_32x32x16_bf16 v[82:97], v[154:157], v[106:109], v[82:97]
	s_waitcnt lgkmcnt(0)
	v_mfma_f32_32x32x16_bf16 v[66:81], v[158:161], v[106:109], v[66:81]
	v_xor_b32_e32 v234, 0x80, v0
	ds_read_b128 v[154:157], v234 offset:32768
	ds_read_b128 v[158:161], v234 offset:40960
	v_or_b32_e32 v0, s97, v196
	v_sub_u32_e32 v0, v190, v0
	v_cmp_lt_i32_e64 s[8:9], 32, v0
	v_cmp_lt_i32_e64 s[12:13], 33, v0
	v_cmp_lt_i32_e64 s[10:11], 1, v0
	v_cmp_lt_i32_e64 s[16:17], 34, v0
	s_waitcnt lgkmcnt(1)
	v_mfma_f32_32x32x16_bf16 v[82:97], v[154:157], v[110:113], v[82:97]
	v_cmp_lt_i32_e64 s[14:15], 2, v0
	v_cmp_lt_i32_e64 s[24:25], 35, v0
	v_cmp_lt_i32_e64 s[22:23], 3, v0
	v_cmp_lt_i32_e64 s[20:21], 40, v0
	v_cmp_lt_i32_e64 s[18:19], 8, v0
	v_cmp_lt_i32_e64 s[28:29], 41, v0
	v_cmp_lt_i32_e64 s[26:27], 9, v0
	s_waitcnt lgkmcnt(0)
	v_mfma_f32_32x32x16_bf16 v[66:81], v[158:161], v[110:113], v[66:81]
	v_xor_b32_e32 v234, 0x80, v162
	ds_read_b128 v[154:157], v234 offset:32768
	ds_read_b128 v[158:161], v234 offset:40960
	v_cmp_lt_i32_e64 s[34:35], 42, v0
	v_cmp_lt_i32_e64 s[30:31], 10, v0
	v_cmp_lt_i32_e64 s[42:43], 43, v0
	v_cmp_lt_i32_e64 s[40:41], 11, v0
	v_cmp_lt_i32_e64 s[38:39], 48, v0
	v_cmp_lt_i32_e64 s[36:37], 16, v0
	s_waitcnt lgkmcnt(1)
	v_mfma_f32_32x32x16_bf16 v[82:97], v[154:157], v[114:117], v[82:97]
	v_cmp_lt_i32_e64 s[46:47], 49, v0
	v_cmp_lt_i32_e64 s[44:45], 17, v0
	v_cmp_lt_i32_e64 s[50:51], 50, v0
	v_cmp_lt_i32_e64 s[48:49], 18, v0
	v_cmp_lt_i32_e64 s[58:59], 51, v0
	v_cmp_lt_i32_e64 s[56:57], 19, v0
	v_cmp_lt_i32_e64 s[54:55], 56, v0
	s_waitcnt lgkmcnt(0)
	v_mfma_f32_32x32x16_bf16 v[66:81], v[158:161], v[114:117], v[66:81]
	v_xor_b32_e32 v234, 0x80, v163
	ds_read_b128 v[154:157], v234 offset:32768
	ds_read_b128 v[158:161], v234 offset:40960
	v_cmp_lt_i32_e64 s[52:53], 24, v0
	v_cmp_lt_i32_e64 s[62:63], 57, v0
	v_cmp_lt_i32_e64 s[60:61], 25, v0
	v_cmp_lt_i32_e64 s[66:67], 58, v0
	v_cmp_lt_i32_e64 s[64:65], 26, v0
	v_cmp_lt_i32_e64 s[68:69], 27, v0
	s_waitcnt lgkmcnt(1)
	v_mfma_f32_32x32x16_bf16 v[82:97], v[154:157], v[118:121], v[82:97]
	v_cmp_lt_i32_e32 vcc, 0, v0
	v_cmp_lt_i32_e64 s[70:71], 59, v0
	s_waitcnt lgkmcnt(0)
	v_mfma_f32_32x32x16_bf16 v[66:81], v[158:161], v[118:121], v[66:81]
	v_xor_b32_e32 v234, 0x80, v164
	ds_read_b128 v[154:157], v234 offset:32768
	ds_read_b128 v[158:161], v234 offset:40960
	s_waitcnt lgkmcnt(1)
	v_mfma_f32_32x32x16_bf16 v[82:97], v[154:157], v[126:129], v[82:97]
	s_waitcnt lgkmcnt(0)
	v_mfma_f32_32x32x16_bf16 v[66:81], v[158:161], v[126:129], v[66:81]
	s_nop 9
	v_exp_f32_e64 v155, -|v82|
	v_max_f32_e32 v154, 0, v82
	v_add_f32_e32 v155, 1.0, v155
	v_log_f32_e32 v155, v155
	v_exp_f32_e64 v156, -|v66|
	v_exp_f32_e64 v157, -|v67|
	v_add_f32_e32 v154, v154, v155
	v_add_f32_e32 v156, 1.0, v156
	v_log_f32_e32 v156, v156
	v_max_f32_e32 v155, 0, v66
	v_add_f32_e32 v157, 1.0, v157
	v_log_f32_e32 v157, v157
	v_add_f32_e32 v155, v155, v156
	v_exp_f32_e64 v156, -|v83|
	v_cndmask_b32_e64 v199, 0, -v155, s[8:9]
	v_max_f32_e32 v155, 0, v83
	v_add_f32_e32 v156, 1.0, v156
	v_log_f32_e32 v156, v156
	v_exp_f32_e64 v158, -|v68|
	v_exp_f32_e64 v159, -|v69|
	v_cndmask_b32_e64 v154, 0, -v154, vcc
	v_add_f32_e32 v155, v155, v156
	v_max_f32_e32 v156, 0, v67
	v_add_f32_e32 v157, v156, v157
	v_cndmask_b32_e64 v200, 0, -v157, s[12:13]
	v_exp_f32_e64 v157, -|v84|
	v_add_f32_e32 v158, 1.0, v158
	v_cndmask_b32_e64 v156, 0, -v155, s[10:11]
	v_add_f32_e32 v157, 1.0, v157
	v_log_f32_e32 v157, v157
	v_log_f32_e32 v158, v158
	v_max_f32_e32 v155, 0, v84
	v_add_f32_e32 v159, 1.0, v159
	v_add_f32_e32 v155, v155, v157
	v_max_f32_e32 v157, 0, v68
	v_add_f32_e32 v157, v157, v158
	v_cndmask_b32_e64 v201, 0, -v157, s[16:17]
	v_exp_f32_e64 v157, -|v85|
	v_cndmask_b32_e64 v158, 0, -v155, s[14:15]
	v_log_f32_e32 v159, v159
	v_add_f32_e32 v157, 1.0, v157
	v_log_f32_e32 v157, v157
	v_max_f32_e32 v155, 0, v85
	v_add_f32_e32 v0, v199, v200
	v_add_f32_e32 v155, v155, v157
	v_max_f32_e32 v157, 0, v69
	v_add_f32_e32 v157, v157, v159
	v_cndmask_b32_e64 v204, 0, -v157, s[24:25]
	v_exp_f32_e64 v157, -|v86|
	v_exp_f32_e64 v159, -|v70|
	v_cndmask_b32_e64 v160, 0, -v155, s[22:23]
	v_add_f32_e32 v157, 1.0, v157
	v_log_f32_e32 v157, v157
	v_add_f32_e32 v159, 1.0, v159
	v_log_f32_e32 v159, v159
	v_max_f32_e32 v155, 0, v86
	v_add_f32_e32 v155, v155, v157
	v_max_f32_e32 v157, 0, v70
	v_add_f32_e32 v157, v157, v159
	v_cndmask_b32_e64 v203, 0, -v157, s[20:21]
	v_exp_f32_e64 v157, -|v87|
	v_exp_f32_e64 v159, -|v71|
	v_cndmask_b32_e64 v202, 0, -v155, s[18:19]
	v_add_f32_e32 v157, 1.0, v157
	v_log_f32_e32 v157, v157
	v_add_f32_e32 v159, 1.0, v159
	v_log_f32_e32 v159, v159
	v_max_f32_e32 v155, 0, v87
	v_add_f32_e32 v155, v155, v157
	v_max_f32_e32 v157, 0, v71
	v_add_f32_e32 v157, v157, v159
	v_cndmask_b32_e64 v206, 0, -v157, s[28:29]
	v_exp_f32_e64 v157, -|v88|
	v_exp_f32_e64 v159, -|v72|
	v_cndmask_b32_e64 v205, 0, -v155, s[26:27]
	v_add_f32_e32 v157, 1.0, v157
	v_log_f32_e32 v157, v157
	v_add_f32_e32 v159, 1.0, v159
	v_log_f32_e32 v159, v159
	v_max_f32_e32 v155, 0, v88
	v_add_f32_e32 v155, v155, v157
	v_max_f32_e32 v157, 0, v72
	v_add_f32_e32 v157, v157, v159
	v_cndmask_b32_e64 v208, 0, -v157, s[34:35]
	v_exp_f32_e64 v157, -|v89|
	v_exp_f32_e64 v159, -|v73|
	v_cndmask_b32_e64 v207, 0, -v155, s[30:31]
	v_add_f32_e32 v157, 1.0, v157
	v_log_f32_e32 v157, v157
	v_add_f32_e32 v159, 1.0, v159
	v_log_f32_e32 v159, v159
	v_max_f32_e32 v155, 0, v89
	v_add_f32_e32 v155, v155, v157
	v_max_f32_e32 v157, 0, v73
	v_add_f32_e32 v157, v157, v159
	v_cndmask_b32_e64 v211, 0, -v157, s[42:43]
	v_exp_f32_e64 v157, -|v90|
	v_exp_f32_e64 v159, -|v74|
	v_cndmask_b32_e64 v210, 0, -v155, s[40:41]
	v_add_f32_e32 v157, 1.0, v157
	v_log_f32_e32 v157, v157
	v_add_f32_e32 v159, 1.0, v159
	v_log_f32_e32 v159, v159
	v_max_f32_e32 v155, 0, v90
	v_add_f32_e32 v155, v155, v157
	v_max_f32_e32 v157, 0, v74
	v_add_f32_e32 v157, v157, v159
	v_cndmask_b32_e64 v162, 0, -v157, s[38:39]
	v_exp_f32_e64 v157, -|v91|
	v_exp_f32_e64 v159, -|v75|
	v_cndmask_b32_e64 v209, 0, -v155, s[36:37]
	v_add_f32_e32 v157, 1.0, v157
	v_log_f32_e32 v157, v157
	v_add_f32_e32 v159, 1.0, v159
	v_log_f32_e32 v159, v159
	v_max_f32_e32 v155, 0, v91
	v_add_f32_e32 v155, v155, v157
	v_max_f32_e32 v157, 0, v75
	v_add_f32_e32 v157, v157, v159
	v_cndmask_b32_e64 v164, 0, -v157, s[46:47]
	v_exp_f32_e64 v157, -|v92|
	v_exp_f32_e64 v159, -|v76|
	v_cndmask_b32_e64 v212, 0, -v155, s[44:45]
	v_add_f32_e32 v157, 1.0, v157
	v_log_f32_e32 v157, v157
	v_add_f32_e32 v159, 1.0, v159
	v_log_f32_e32 v159, v159
	v_max_f32_e32 v155, 0, v92
	v_add_f32_e32 v155, v155, v157
	v_max_f32_e32 v157, 0, v76
	v_add_f32_e32 v157, v157, v159
	v_cndmask_b32_e64 v214, 0, -v157, s[50:51]
	v_exp_f32_e64 v157, -|v93|
	v_exp_f32_e64 v159, -|v77|
	v_cndmask_b32_e64 v213, 0, -v155, s[48:49]
	v_add_f32_e32 v157, 1.0, v157
	v_log_f32_e32 v157, v157
	v_add_f32_e32 v159, 1.0, v159
	v_log_f32_e32 v159, v159
	v_max_f32_e32 v155, 0, v93
	v_add_f32_e32 v155, v155, v157
	v_max_f32_e32 v157, 0, v77
	v_add_f32_e32 v157, v157, v159
	v_cndmask_b32_e64 v217, 0, -v157, s[58:59]
	v_exp_f32_e64 v157, -|v94|
	v_exp_f32_e64 v159, -|v78|
	v_cndmask_b32_e64 v216, 0, -v155, s[56:57]
	v_add_f32_e32 v157, 1.0, v157
	v_log_f32_e32 v157, v157
	v_add_f32_e32 v159, 1.0, v159
	v_log_f32_e32 v159, v159
	v_max_f32_e32 v155, 0, v94
	v_add_f32_e32 v155, v155, v157
	v_max_f32_e32 v157, 0, v78
	v_add_f32_e32 v157, v157, v159
	v_cndmask_b32_e64 v215, 0, -v157, s[54:55]
	v_exp_f32_e64 v157, -|v95|
	v_exp_f32_e64 v159, -|v79|
	v_cndmask_b32_e64 v168, 0, -v155, s[52:53]
	v_add_f32_e32 v157, 1.0, v157
	v_log_f32_e32 v157, v157
	v_add_f32_e32 v159, 1.0, v159
	v_log_f32_e32 v159, v159
	v_max_f32_e32 v155, 0, v95
	v_add_f32_e32 v155, v155, v157
	v_max_f32_e32 v157, 0, v79
	v_add_f32_e32 v157, v157, v159
	v_cndmask_b32_e64 v220, 0, -v157, s[62:63]
	v_exp_f32_e64 v157, -|v96|
	v_exp_f32_e64 v159, -|v80|
	v_cndmask_b32_e64 v170, 0, -v155, s[60:61]
	v_add_f32_e32 v157, 1.0, v157
	v_log_f32_e32 v157, v157
	v_add_f32_e32 v159, 1.0, v159
	v_log_f32_e32 v159, v159
	v_max_f32_e32 v155, 0, v96
	v_add_f32_e32 v155, v155, v157
	v_max_f32_e32 v157, 0, v80
	v_add_f32_e32 v157, v157, v159
	v_cndmask_b32_e64 v221, 0, -v157, s[66:67]
	v_exp_f32_e64 v157, -|v97|
	v_exp_f32_e64 v159, -|v81|
	v_cndmask_b32_e64 v172, 0, -v155, s[64:65]
	v_add_f32_e32 v157, 1.0, v157
	v_log_f32_e32 v157, v157
	v_add_f32_e32 v159, 1.0, v159
	v_log_f32_e32 v159, v159
	v_max_f32_e32 v155, 0, v97
	v_add_f32_e32 v155, v155, v157
	v_max_f32_e32 v157, 0, v81
	v_cndmask_b32_e64 v174, 0, -v155, s[68:69]
	v_add_f32_e32 v155, v201, v204
	v_add_f32_e32 v157, v157, v159
	v_add_f32_e32 v169, v0, v155
	v_add_f32_e32 v0, v202, v205
	v_add_f32_e32 v155, v207, v210
	v_cndmask_b32_e64 v222, 0, -v157, s[70:71]
	v_add_f32_e32 v155, v0, v155
	v_add_f32_e32 v0, v203, v206
	v_add_f32_e32 v157, v208, v211
	v_add_f32_e32 v159, v0, v157
	v_add_f32_e32 v0, v209, v212
	v_add_f32_e32 v157, v213, v216
	v_add_f32_e32 v223, v0, v157
	v_mov_b32_e32 v0, v155
	v_mov_b32_e32 v157, v155
	s_nop 1
	v_permlane32_swap_b32_e32 v0, v157
	v_cndmask_b32_e64 v157, v0, v157, s[4:5]
	v_mov_b32_e32 v0, v223
	v_mov_b32_e32 v161, v223
	s_nop 1
	v_permlane32_swap_b32_e32 v0, v161
	v_cndmask_b32_e64 v224, v0, v161, s[4:5]
	v_mov_b32_e32 v0, v169
	v_mov_b32_e32 v161, v169
	s_nop 1
	v_permlane32_swap_b32_e32 v0, v161
	v_add_f32_e32 v163, v215, v220
	v_add_f32_e32 v165, v221, v222
	v_cndmask_b32_e64 v171, v0, v161, s[4:5]
	v_mov_b32_e32 v0, v159
	v_mov_b32_e32 v161, v159
	s_nop 1
	v_permlane32_swap_b32_e32 v0, v161
	v_pk_add_f32 v[218:219], v[162:163], v[164:165]
	v_cndmask_b32_e64 v161, v0, v161, s[4:5]
	v_mov_b32_e32 v0, v219
	v_mov_b32_e32 v163, v219
	s_nop 1
	v_permlane32_swap_b32_e32 v0, v163
	v_add_f32_e32 v176, v214, v217
	v_cndmask_b32_e64 v177, v0, v163, s[4:5]
	v_pk_add_f32 v[218:219], v[218:219], v[176:177]
	v_add_f32_e32 v173, v159, v161
	v_mov_b32_e32 v0, v218
	v_mov_b32_e32 v163, v218
	s_nop 1
	v_permlane32_swap_b32_e32 v0, v163
	v_cndmask_b32_e64 v0, v0, v163, s[4:5]
	v_add_f32_e32 v163, 0, v177
	v_cndmask_b32_e64 v165, 0, v0, s[4:5]
	v_pk_add_f32 v[176:177], v[218:219], v[0:1]
	v_pk_add_f32 v[218:219], v[168:169], v[170:171]
	v_add_f32_e32 v0, v165, v177
	v_pk_add_f32 v[176:177], v[176:177], v[176:177] op_sel:[0,1] op_sel_hi:[1,0]
	v_cndmask_b32_e64 v165, 0, v161, s[4:5]
	v_mov_b32_e32 v175, v176
	v_add_f32_e32 v165, v165, v176
	v_pk_add_f32 v[176:177], v[172:173], v[174:175]
	v_cndmask_b32_e64 v159, 0, v171, s[4:5]
	v_pk_add_f32 v[218:219], v[218:219], v[176:177]
	v_cndmask_b32_e64 v175, 0, v157, s[4:5]
	v_mov_b32_e32 v161, v218
	v_mov_b32_e32 v169, v218
	s_nop 1
	v_permlane32_swap_b32_e32 v161, v169
	v_cndmask_b32_e64 v161, v161, v169, s[4:5]
	v_add_f32_e32 v169, v159, v177
	v_cndmask_b32_e64 v159, 0, v161, s[4:5]
	v_add_f32_e32 v171, v159, v219
	v_add_f32_e32 v159, v218, v161
	v_add_f32_e32 v161, v159, v219
	v_cndmask_b32_e64 v159, 0, v224, s[4:5]
	v_add_f32_e32 v173, v159, v161
	v_add_f32_e32 v159, v223, v224
	v_pk_add_f32 v[218:219], v[158:159], v[160:161]
	v_pk_add_f32 v[176:177], v[154:155], v[156:157]
	v_add_f32_e32 v161, v198, v169
	v_pk_add_f32 v[176:177], v[176:177], v[218:219]
	v_add_f32_e32 v0, v198, v0
	v_mov_b32_e32 v155, v176
	v_mov_b32_e32 v157, v176
	s_nop 1
	v_permlane32_swap_b32_e32 v155, v157
	v_cndmask_b32_e64 v155, v155, v157, s[4:5]
	v_cndmask_b32_e64 v159, 0, v155, s[4:5]
	v_add_f32_e32 v159, v159, v177
	v_add_f32_e32 v159, v198, v159
	v_add_f32_e32 v159, v160, v159
	v_add_f32_e32 v160, v204, v161
	v_add_f32_e32 v69, v69, v160
	v_exp_f32_e32 v69, v69
	v_add_f32_e32 v85, v85, v159
	v_add_f32_e32 v157, v175, v219
	v_add_f32_e32 v0, v217, v0
	v_cndmask_b32_e64 v161, 0, v69, s[24:25]
	v_add_f32_e32 v69, v158, v159
	v_add_f32_e32 v158, v201, v160
	v_add_f32_e32 v68, v68, v158
	v_exp_f32_e32 v68, v68
	v_add_f32_e32 v84, v84, v69
	v_cndmask_b32_e64 v163, 0, v163, s[4:5]
	v_exp_f32_e32 v85, v85
	v_cndmask_b32_e64 v159, 0, v68, s[16:17]
	v_add_f32_e32 v68, v156, v69
	v_add_f32_e32 v69, v200, v158
	v_add_f32_e32 v67, v67, v69
	v_exp_f32_e32 v67, v67
	v_add_f32_e32 v83, v83, v68
	v_exp_f32_e32 v84, v84
	v_exp_f32_e32 v83, v83
	v_cndmask_b32_e64 v156, 0, v67, s[12:13]
	v_add_f32_e32 v67, v154, v68
	v_add_f32_e32 v68, v199, v69
	v_add_f32_e32 v66, v66, v68
	v_exp_f32_e32 v66, v66
	v_add_f32_e32 v68, v198, v165
	v_add_f32_e32 v68, v211, v68
	v_add_f32_e32 v73, v73, v68
	v_add_f32_e32 v68, v208, v68
	v_exp_f32_e32 v73, v73
	v_add_f32_e32 v72, v72, v68
	v_add_f32_e32 v67, v82, v67
	v_cndmask_b32_e64 v82, 0, v66, s[8:9]
	v_add_f32_e32 v66, v198, v157
	v_exp_f32_e32 v72, v72
	v_add_f32_e32 v66, v210, v66
	v_add_f32_e32 v69, v89, v66
	v_add_f32_e32 v66, v207, v66
	v_cndmask_b32_e64 v89, 0, v73, s[42:43]
	v_add_f32_e32 v73, v88, v66
	v_add_f32_e32 v66, v205, v66
	v_cndmask_b32_e64 v88, 0, v72, s[34:35]
	v_add_f32_e32 v72, v87, v66
	v_add_f32_e32 v66, v202, v66
	v_add_f32_e32 v68, v206, v68
	v_add_f32_e32 v66, v86, v66
	v_add_f32_e32 v71, v71, v68
	v_add_f32_e32 v68, v203, v68
	v_exp_f32_e32 v66, v66
	v_add_f32_e32 v68, v70, v68
	v_exp_f32_e32 v68, v68
	v_exp_f32_e32 v71, v71
	v_cndmask_b32_e64 v70, 0, v66, s[18:19]
	v_add_f32_e32 v66, v198, v173
	v_add_f32_e32 v66, v216, v66
	v_cndmask_b32_e64 v86, 0, v68, s[20:21]
	v_add_f32_e32 v68, v93, v66
	v_exp_f32_e32 v68, v68
	v_cndmask_b32_e64 v87, 0, v71, s[28:29]
	v_add_f32_e32 v71, v77, v0
	v_add_f32_e32 v66, v213, v66
	v_exp_f32_e32 v71, v71
	v_cndmask_b32_e64 v77, 0, v68, s[56:57]
	v_add_f32_e32 v68, v92, v66
	v_exp_f32_e32 v68, v68
	v_add_f32_e32 v0, v214, v0
	v_cndmask_b32_e64 v93, 0, v71, s[58:59]
	v_add_f32_e32 v71, v76, v0
	v_add_f32_e32 v66, v212, v66
	v_exp_f32_e32 v71, v71
	v_cndmask_b32_e64 v76, 0, v68, s[48:49]
	v_add_f32_e32 v68, v91, v66
	v_exp_f32_e32 v68, v68
	v_add_f32_e32 v0, v164, v0
	v_add_f32_e32 v66, v209, v66
	v_cndmask_b32_e64 v92, 0, v71, s[50:51]
	v_add_f32_e32 v71, v75, v0
	v_add_f32_e32 v66, v90, v66
	v_exp_f32_e32 v71, v71
	v_cndmask_b32_e64 v75, 0, v68, s[44:45]
	v_exp_f32_e32 v66, v66
	v_add_f32_e32 v68, v198, v163
	v_add_f32_e32 v68, v222, v68
	v_add_f32_e32 v81, v81, v68
	v_add_f32_e32 v68, v221, v68
	v_add_f32_e32 v80, v80, v68
	v_cndmask_b32_e64 v91, 0, v71, s[46:47]
	v_cndmask_b32_e64 v71, 0, v66, s[36:37]
	v_add_f32_e32 v66, v198, v171
	v_exp_f32_e32 v80, v80
	v_add_f32_e32 v0, v162, v0
	v_add_f32_e32 v66, v174, v66
	v_add_f32_e32 v0, v74, v0
	v_add_f32_e32 v74, v97, v66
	v_add_f32_e32 v66, v172, v66
	v_add_f32_e32 v90, v96, v66
	v_add_f32_e32 v66, v170, v66
	v_add_f32_e32 v68, v220, v68
	v_cndmask_b32_e64 v96, 0, v80, s[66:67]
	v_add_f32_e32 v80, v95, v66
	v_add_f32_e32 v79, v79, v68
	v_add_f32_e32 v66, v168, v66
	v_add_f32_e32 v68, v215, v68
	v_add_f32_e32 v66, v94, v66
	v_add_f32_e32 v68, v78, v68
	v_exp_f32_e32 v67, v67
	v_exp_f32_e32 v69, v69
	v_exp_f32_e32 v73, v73
	v_exp_f32_e32 v72, v72
	v_exp_f32_e32 v0, v0
	v_exp_f32_e32 v74, v74
	v_exp_f32_e32 v81, v81
	v_exp_f32_e32 v90, v90
	v_exp_f32_e32 v80, v80
	v_exp_f32_e32 v79, v79
	v_exp_f32_e32 v66, v66
	v_exp_f32_e32 v68, v68
	v_add_f32_e32 v155, v176, v155
	v_cndmask_b32_e64 v85, 0, v85, s[22:23]
	v_cndmask_b32_e64 v84, 0, v84, s[14:15]
	v_cndmask_b32_e64 v83, 0, v83, s[10:11]
	v_cndmask_b32_e32 v67, 0, v67, vcc
	v_cndmask_b32_e64 v69, 0, v69, s[40:41]
	v_cndmask_b32_e64 v73, 0, v73, s[30:31]
	v_cndmask_b32_e64 v72, 0, v72, s[26:27]
	v_cndmask_b32_e64 v0, 0, v0, s[38:39]
	v_cndmask_b32_e64 v74, 0, v74, s[68:69]
	v_cndmask_b32_e64 v81, 0, v81, s[70:71]
	v_cndmask_b32_e64 v90, 0, v90, s[64:65]
	v_cndmask_b32_e64 v80, 0, v80, s[60:61]
	v_cndmask_b32_e64 v95, 0, v79, s[62:63]
	v_cndmask_b32_e64 v78, 0, v66, s[52:53]
	v_cndmask_b32_e64 v94, 0, v68, s[54:55]
	v_add_f32_e32 v66, v155, v177
	v_add_f32_e32 v198, v198, v66
	v_cvt_pk_bf16_f32 v66, v67, v83
	v_cvt_pk_bf16_f32 v67, v84, v85
	v_cvt_pk_bf16_f32 v68, v70, v72
	v_cvt_pk_bf16_f32 v69, v73, v69
	v_cvt_pk_bf16_f32 v70, v71, v75
	v_cvt_pk_bf16_f32 v71, v76, v77
	v_cvt_pk_bf16_f32 v72, v78, v80
	v_cvt_pk_bf16_f32 v73, v90, v74
	v_cvt_pk_bf16_f32 v74, v82, v156
	v_cvt_pk_bf16_f32 v75, v159, v161
	v_cvt_pk_bf16_f32 v76, v86, v87
	v_cvt_pk_bf16_f32 v77, v88, v89
	v_cvt_pk_bf16_f32 v78, v0, v91
	v_cvt_pk_bf16_f32 v79, v92, v93
	v_cvt_pk_bf16_f32 v80, v94, v95
	v_cvt_pk_bf16_f32 v81, v96, v81
	v_permlane32_swap_b32_e32 v66, v68
	v_permlane32_swap_b32_e32 v67, v69
	v_permlane32_swap_b32_e32 v70, v72
	v_permlane32_swap_b32_e32 v71, v73
	v_permlane32_swap_b32_e32 v74, v76
	v_permlane32_swap_b32_e32 v75, v77
	v_permlane32_swap_b32_e32 v78, v80
	v_permlane32_swap_b32_e32 v79, v81
	v_add_u32_e32 v0, s33, v197
	ds_read_b64_tr_b16 v[82:83], v0 offset:0
	ds_read_b64_tr_b16 v[84:85], v0 offset:0x800
	ds_read_b64_tr_b16 v[86:87], v0 offset:0x1000
	ds_read_b64_tr_b16 v[88:89], v0 offset:0x1800
	ds_read_b64_tr_b16 v[90:91], v0 offset:0x2000
	ds_read_b64_tr_b16 v[92:93], v0 offset:0x2800
	ds_read_b64_tr_b16 v[94:95], v0 offset:0x3000
	ds_read_b64_tr_b16 v[96:97], v0 offset:0x3800
	s_waitcnt lgkmcnt(0)
	s_nop 0
	v_mfma_f32_32x32x16_bf16 v[2:17], v[66:69], v[82:85], v[2:17]
	ds_read_b64_tr_b16 v[82:83], v0 offset:0x200
	ds_read_b64_tr_b16 v[84:85], v0 offset:0xa00
	v_mfma_f32_32x32x16_bf16 v[2:17], v[70:73], v[86:89], v[2:17]
	ds_read_b64_tr_b16 v[86:87], v0 offset:0x1200
	ds_read_b64_tr_b16 v[88:89], v0 offset:0x1a00
	v_mfma_f32_32x32x16_bf16 v[2:17], v[74:77], v[90:93], v[2:17]
	ds_read_b64_tr_b16 v[90:91], v0 offset:0x2200
	ds_read_b64_tr_b16 v[92:93], v0 offset:0x2a00
	ds_read_b64_tr_b16 v[154:155], v0 offset:0x3200
	ds_read_b64_tr_b16 v[156:157], v0 offset:0x3a00
	s_waitcnt lgkmcnt(0)
	v_mfma_f32_32x32x16_bf16 v[2:17], v[78:81], v[94:97], v[2:17]
	v_mfma_f32_32x32x16_bf16 v[18:33], v[66:69], v[82:85], v[18:33]
	ds_read_b64_tr_b16 v[82:83], v0 offset:0x400
	ds_read_b64_tr_b16 v[84:85], v0 offset:0xc00
	v_mfma_f32_32x32x16_bf16 v[18:33], v[70:73], v[86:89], v[18:33]
	ds_read_b64_tr_b16 v[86:87], v0 offset:0x1400
	ds_read_b64_tr_b16 v[88:89], v0 offset:0x1c00
	v_mfma_f32_32x32x16_bf16 v[18:33], v[74:77], v[90:93], v[18:33]
	ds_read_b64_tr_b16 v[90:91], v0 offset:0x2400
	ds_read_b64_tr_b16 v[92:93], v0 offset:0x2c00
	ds_read_b64_tr_b16 v[94:95], v0 offset:0x3400
	ds_read_b64_tr_b16 v[96:97], v0 offset:0x3c00
	s_waitcnt lgkmcnt(0)
	v_mfma_f32_32x32x16_bf16 v[18:33], v[78:81], v[154:157], v[18:33]
	v_mfma_f32_32x32x16_bf16 v[34:49], v[66:69], v[82:85], v[34:49]
	ds_read_b64_tr_b16 v[82:83], v0 offset:0x600
	ds_read_b64_tr_b16 v[84:85], v0 offset:0xe00
	v_mfma_f32_32x32x16_bf16 v[34:49], v[70:73], v[86:89], v[34:49]
	ds_read_b64_tr_b16 v[86:87], v0 offset:0x1600
	ds_read_b64_tr_b16 v[88:89], v0 offset:0x1e00
	v_mfma_f32_32x32x16_bf16 v[34:49], v[74:77], v[90:93], v[34:49]
	ds_read_b64_tr_b16 v[90:91], v0 offset:0x2600
	ds_read_b64_tr_b16 v[92:93], v0 offset:0x2e00
	ds_read_b64_tr_b16 v[154:155], v0 offset:0x3600
	ds_read_b64_tr_b16 v[156:157], v0 offset:0x3e00
	s_waitcnt lgkmcnt(0)
	v_mfma_f32_32x32x16_bf16 v[34:49], v[78:81], v[94:97], v[34:49]
	v_mfma_f32_32x32x16_bf16 v[50:65], v[66:69], v[82:85], v[50:65]
	v_cmp_gt_f32_e32 vcc, s79, v198
	s_cmp_eq_u64 vcc, exec
	s_cselect_b64 s[8:9], -1, 0
	v_mfma_f32_32x32x16_bf16 v[50:65], v[70:73], v[86:89], v[50:65]
	v_mfma_f32_32x32x16_bf16 v[50:65], v[74:77], v[90:93], v[50:65]
	v_mfma_f32_32x32x16_bf16 v[50:65], v[78:81], v[154:157], v[50:65]
	s_and_saveexec_b64 s[10:11], s[6:7]
	s_cbranch_execz .LBB0_698
